# FFN-out fused epilogue: residual added into the accumulators in pass 1, so pass 2 (hand-written) no longer re-loads/unpacks/re-adds h: y = acc*r*g
# speedup vs baseline: 1.0285x; 1.0041x over previous
.LBB0_702:
	s_andn2_b64 vcc, exec, s[50:51]
	s_cbranch_vccnz .LBB0_740
	v_lshlrev_b32_e32 v130, 1, v182
	v_lshl_add_u32 v170, v180, 11, v130
	v_or_b32_e32 v188, 0x100, v170
	global_load_dwordx4 v[190:193], v170, s[40:41]
	global_load_dwordx4 v[194:197], v188, s[40:41]
	v_add_u32_e32 v186, 0x8000, v170
	v_add_u32_e32 v184, 0x8100, v170
	v_add_u32_e32 v160, 0x10000, v170
	v_add_u32_e32 v158, 0x10100, v170
	v_add_u32_e32 v156, 0x18000, v170
	v_add_u32_e32 v154, 0x18100, v170
	global_load_dwordx4 v[150:153], v186, s[40:41]
	global_load_dwordx4 v[146:149], v184, s[40:41]
	global_load_dwordx4 v[142:145], v160, s[40:41]
	global_load_dwordx4 v[138:141], v158, s[40:41]
	global_load_dwordx4 v[134:137], v156, s[40:41]
	global_load_dwordx4 v[130:133], v154, s[40:41]
	v_and_b32_e32 v157, 64, v211
	v_xor_b32_e32 v155, 16, v211
	v_add_u32_e32 v157, 64, v157
	v_cmp_lt_i32_e32 vcc, v155, v157
	s_waitcnt vmcnt(0)
	v_lshlrev_b32_e32 v198, 16, v190
	v_and_b32_e32 v199, 0xffff0000, v190
	v_lshlrev_b32_e32 v190, 16, v191
	v_and_b32_e32 v191, 0xffff0000, v191
	v_lshlrev_b32_e32 v202, 16, v194
	v_and_b32_e32 v203, 0xffff0000, v194
	v_lshlrev_b32_e32 v194, 16, v195
	v_and_b32_e32 v195, 0xffff0000, v195
	v_lshlrev_b32_e32 v200, 16, v192
	v_and_b32_e32 v201, 0xffff0000, v192
	v_pk_add_f32 v[128:129], v[128:129], v[190:191]
	v_pk_add_f32 v[126:127], v[126:127], v[198:199]
	v_lshlrev_b32_e32 v204, 16, v196
	v_and_b32_e32 v205, 0xffff0000, v196
	v_pk_add_f32 v[112:113], v[112:113], v[194:195]
	v_pk_add_f32 v[110:111], v[110:111], v[202:203]
	v_lshlrev_b32_e32 v192, 16, v193
	v_and_b32_e32 v193, 0xffff0000, v193
	v_pk_add_f32 v[122:123], v[122:123], v[200:201]
	v_lshlrev_b32_e32 v196, 16, v197
	v_and_b32_e32 v197, 0xffff0000, v197
	v_mul_f32_e32 v159, v127, v127
	v_mul_f32_e32 v161, v129, v129
	v_pk_add_f32 v[106:107], v[106:107], v[204:205]
	v_mul_f32_e32 v185, v111, v111
	v_mul_f32_e32 v187, v113, v113
	v_pk_add_f32 v[124:125], v[124:125], v[192:193]
	v_mul_f32_e32 v181, v123, v123
	v_pk_add_f32 v[108:109], v[108:109], v[196:197]
	v_fmac_f32_e32 v159, v126, v126
	v_fmac_f32_e32 v161, v128, v128
	v_mul_f32_e32 v189, v107, v107
	v_fmac_f32_e32 v185, v110, v110
	v_fmac_f32_e32 v187, v112, v112
	v_mul_f32_e32 v183, v125, v125
	v_fmac_f32_e32 v181, v122, v122
	v_mul_f32_e32 v190, v109, v109
	v_add_f32_e32 v159, v159, v161
	v_fmac_f32_e32 v189, v106, v106
	v_add_f32_e32 v161, v185, v187
	v_fmac_f32_e32 v183, v124, v124
	v_add_f32_e32 v159, v181, v159
	v_add_f32_e32 v161, v189, v161
	v_fmac_f32_e32 v190, v108, v108
	v_cndmask_b32_e32 v155, v211, v155, vcc
	v_add_f32_e32 v159, v183, v159
	v_add_f32_e32 v161, v190, v161
	v_lshlrev_b32_e32 v155, 2, v155
	v_add_f32_e32 v159, v159, v161
	ds_bpermute_b32 v161, v155, v159
	v_xor_b32_e32 v181, 32, v211
	v_cmp_lt_i32_e32 vcc, v181, v157
	s_waitcnt lgkmcnt(0)
	v_add_f32_e32 v159, v159, v161
	v_cndmask_b32_e32 v157, v211, v181, vcc
	v_lshlrev_b32_e32 v157, 2, v157
	ds_bpermute_b32 v161, v157, v159
	s_and_saveexec_b64 s[50:51], s[4:5]
	s_cbranch_execz .LBB0_705
	s_waitcnt lgkmcnt(0)
	v_add_f32_e32 v159, v159, v161
	ds_write_b32 v218, v159
.LBB0_705:
	s_or_b64 exec, exec, s[50:51]
	v_lshlrev_b32_e32 v190, 16, v150
	v_and_b32_e32 v191, 0xffff0000, v150
	v_lshlrev_b32_e32 v150, 16, v151
	v_and_b32_e32 v151, 0xffff0000, v151
	v_pk_add_f32 v[120:121], v[120:121], v[150:151]
	v_pk_add_f32 v[118:119], v[118:119], v[190:191]
	v_lshlrev_b32_e32 v192, 16, v152
	v_and_b32_e32 v193, 0xffff0000, v152
	v_mul_f32_e32 v159, v119, v119
	v_mul_f32_e32 v151, v121, v121
	v_pk_add_f32 v[114:115], v[114:115], v[192:193]
	v_fmac_f32_e32 v159, v118, v118
	v_fmac_f32_e32 v151, v120, v120
	v_lshlrev_b32_e32 v152, 16, v153
	v_and_b32_e32 v153, 0xffff0000, v153
	v_add_f32_e32 v150, v159, v151
	v_mul_f32_e32 v151, v115, v115
	v_pk_add_f32 v[116:117], v[116:117], v[152:153]
	v_fmac_f32_e32 v151, v114, v114
	v_add_f32_e32 v150, v151, v150
	v_mul_f32_e32 v151, v117, v117
	v_fmac_f32_e32 v151, v116, v116
	v_add_f32_e32 v159, v151, v150
	v_lshlrev_b32_e32 v150, 16, v146
	v_and_b32_e32 v151, 0xffff0000, v146
	v_lshlrev_b32_e32 v146, 16, v147
	v_and_b32_e32 v147, 0xffff0000, v147
	v_pk_add_f32 v[96:97], v[96:97], v[146:147]
	v_pk_add_f32 v[94:95], v[94:95], v[150:151]
	v_lshlrev_b32_e32 v152, 16, v148
	v_and_b32_e32 v153, 0xffff0000, v148
	v_mul_f32_e32 v151, v95, v95
	v_mul_f32_e32 v147, v97, v97
	v_pk_add_f32 v[90:91], v[90:91], v[152:153]
	v_fmac_f32_e32 v151, v94, v94
	v_fmac_f32_e32 v147, v96, v96
	v_lshlrev_b32_e32 v148, 16, v149
	v_and_b32_e32 v149, 0xffff0000, v149
	v_add_f32_e32 v146, v151, v147
	v_mul_f32_e32 v147, v91, v91
	v_pk_add_f32 v[92:93], v[92:93], v[148:149]
	v_fmac_f32_e32 v147, v90, v90
	v_add_f32_e32 v146, v147, v146
	v_mul_f32_e32 v147, v93, v93
	v_fmac_f32_e32 v147, v92, v92
	v_add_f32_e32 v146, v147, v146
	v_add_f32_e32 v146, v159, v146
	ds_bpermute_b32 v147, v155, v146
	s_waitcnt lgkmcnt(0)
	v_add_f32_e32 v146, v146, v147
	ds_bpermute_b32 v147, v157, v146
	s_and_saveexec_b64 s[50:51], s[4:5]
	s_cbranch_execz .LBB0_707
	s_waitcnt lgkmcnt(0)
	v_add_f32_e32 v146, v146, v147
	ds_write_b32 v218, v146 offset:256
.LBB0_707:
	s_or_b64 exec, exec, s[50:51]
	v_lshlrev_b32_e32 v146, 16, v142
	s_waitcnt lgkmcnt(0)
	v_and_b32_e32 v147, 0xffff0000, v142
	v_lshlrev_b32_e32 v142, 16, v143
	v_and_b32_e32 v143, 0xffff0000, v143
	v_pk_add_f32 v[104:105], v[104:105], v[142:143]
	v_pk_add_f32 v[102:103], v[102:103], v[146:147]
	v_lshlrev_b32_e32 v148, 16, v144
	v_and_b32_e32 v149, 0xffff0000, v144
	v_mul_f32_e32 v147, v103, v103
	v_mul_f32_e32 v143, v105, v105
	v_pk_add_f32 v[98:99], v[98:99], v[148:149]
	v_fmac_f32_e32 v147, v102, v102
	v_fmac_f32_e32 v143, v104, v104
	v_lshlrev_b32_e32 v144, 16, v145
	v_and_b32_e32 v145, 0xffff0000, v145
	v_add_f32_e32 v142, v147, v143
	v_mul_f32_e32 v143, v99, v99
	v_pk_add_f32 v[100:101], v[100:101], v[144:145]
	v_fmac_f32_e32 v143, v98, v98
	v_add_f32_e32 v142, v143, v142
	v_mul_f32_e32 v143, v101, v101
	v_fmac_f32_e32 v143, v100, v100
	v_add_f32_e32 v146, v143, v142
	v_lshlrev_b32_e32 v142, 16, v138
	v_and_b32_e32 v143, 0xffff0000, v138
	v_lshlrev_b32_e32 v138, 16, v139
	v_and_b32_e32 v139, 0xffff0000, v139
	v_pk_add_f32 v[80:81], v[80:81], v[138:139]
	v_pk_add_f32 v[78:79], v[78:79], v[142:143]
	v_lshlrev_b32_e32 v144, 16, v140
	v_and_b32_e32 v145, 0xffff0000, v140
	v_mul_f32_e32 v143, v79, v79
	v_mul_f32_e32 v139, v81, v81
	v_pk_add_f32 v[74:75], v[74:75], v[144:145]
	v_fmac_f32_e32 v143, v78, v78
	v_fmac_f32_e32 v139, v80, v80
	v_lshlrev_b32_e32 v140, 16, v141
	v_and_b32_e32 v141, 0xffff0000, v141
	v_add_f32_e32 v138, v143, v139
	v_mul_f32_e32 v139, v75, v75
	v_pk_add_f32 v[76:77], v[76:77], v[140:141]
	v_fmac_f32_e32 v139, v74, v74
	v_add_f32_e32 v138, v139, v138
	v_mul_f32_e32 v139, v77, v77
	v_fmac_f32_e32 v139, v76, v76
	v_add_f32_e32 v138, v139, v138
	v_add_f32_e32 v138, v146, v138
	ds_bpermute_b32 v139, v155, v138
	s_waitcnt lgkmcnt(0)
	v_add_f32_e32 v138, v138, v139
	ds_bpermute_b32 v139, v157, v138
	s_and_saveexec_b64 s[50:51], s[4:5]
	s_cbranch_execz .LBB0_709
	s_waitcnt lgkmcnt(0)
	v_add_f32_e32 v138, v138, v139
	ds_write_b32 v218, v138 offset:512
.LBB0_709:
	s_or_b64 exec, exec, s[50:51]
	v_lshlrev_b32_e32 v138, 16, v134
	s_waitcnt lgkmcnt(0)
	v_and_b32_e32 v139, 0xffff0000, v134
	v_lshlrev_b32_e32 v134, 16, v135
	v_and_b32_e32 v135, 0xffff0000, v135
	v_pk_add_f32 v[88:89], v[88:89], v[134:135]
	v_pk_add_f32 v[86:87], v[86:87], v[138:139]
	v_lshlrev_b32_e32 v140, 16, v136
	v_and_b32_e32 v141, 0xffff0000, v136
	v_mul_f32_e32 v139, v87, v87
	v_mul_f32_e32 v135, v89, v89
	v_pk_add_f32 v[82:83], v[82:83], v[140:141]
	v_fmac_f32_e32 v139, v86, v86
	v_fmac_f32_e32 v135, v88, v88
	v_lshlrev_b32_e32 v136, 16, v137
	v_and_b32_e32 v137, 0xffff0000, v137
	v_add_f32_e32 v134, v139, v135
	v_mul_f32_e32 v135, v83, v83
	v_pk_add_f32 v[84:85], v[84:85], v[136:137]
	v_fmac_f32_e32 v135, v82, v82
	v_add_f32_e32 v134, v135, v134
	v_mul_f32_e32 v135, v85, v85
	v_fmac_f32_e32 v135, v84, v84
	v_add_f32_e32 v138, v135, v134
	v_lshlrev_b32_e32 v134, 16, v130
	v_and_b32_e32 v135, 0xffff0000, v130
	v_lshlrev_b32_e32 v130, 16, v131
	v_and_b32_e32 v131, 0xffff0000, v131
	v_pk_add_f32 v[72:73], v[72:73], v[130:131]
	v_pk_add_f32 v[70:71], v[70:71], v[134:135]
	v_lshlrev_b32_e32 v136, 16, v132
	v_and_b32_e32 v137, 0xffff0000, v132
	v_mul_f32_e32 v135, v71, v71
	v_mul_f32_e32 v131, v73, v73
	v_pk_add_f32 v[66:67], v[66:67], v[136:137]
	v_fmac_f32_e32 v135, v70, v70
	v_fmac_f32_e32 v131, v72, v72
	v_lshlrev_b32_e32 v132, 16, v133
	v_and_b32_e32 v133, 0xffff0000, v133
	v_add_f32_e32 v130, v135, v131
	v_mul_f32_e32 v131, v67, v67
	v_pk_add_f32 v[68:69], v[68:69], v[132:133]
	v_fmac_f32_e32 v131, v66, v66
	v_add_f32_e32 v130, v131, v130
	v_mul_f32_e32 v131, v69, v69
	v_fmac_f32_e32 v131, v68, v68
	v_add_f32_e32 v130, v131, v130
	v_add_f32_e32 v130, v138, v130
	ds_bpermute_b32 v131, v155, v130
	s_waitcnt lgkmcnt(0)
	v_add_f32_e32 v130, v130, v131
	ds_bpermute_b32 v131, v157, v130
	s_and_saveexec_b64 s[50:51], s[4:5]
	s_cbranch_execz .LBB0_711
	s_waitcnt lgkmcnt(0)
	v_add_f32_e32 v130, v130, v131
	ds_write_b32 v218, v130 offset:768
.LBB0_711:
	s_or_b64 exec, exec, s[50:51]
	v_add_u32_e32 v204, 0x40000, v170
	v_add_u32_e32 v202, 0x40100, v170
	global_load_dwordx4 v[220:223], v204, s[40:41]
	global_load_dwordx4 v[224:227], v202, s[40:41]
	v_add_u32_e32 v200, 0x48000, v170
	v_add_u32_e32 v198, 0x48100, v170
	v_add_u32_e32 v196, 0x50000, v170
	v_add_u32_e32 v194, 0x50100, v170
	v_add_u32_e32 v192, 0x58000, v170
	v_add_u32_e32 v190, 0x58100, v170
	global_load_dwordx4 v[150:153], v200, s[40:41]
	global_load_dwordx4 v[146:149], v198, s[40:41]
	global_load_dwordx4 v[142:145], v196, s[40:41]
	global_load_dwordx4 v[138:141], v194, s[40:41]
	global_load_dwordx4 v[134:137], v192, s[40:41]
	s_waitcnt lgkmcnt(0)
	global_load_dwordx4 v[130:133], v190, s[40:41]
	s_waitcnt vmcnt(7)
	v_lshlrev_b32_e32 v206, 16, v220
	v_and_b32_e32 v207, 0xffff0000, v220
	v_lshlrev_b32_e32 v220, 16, v221
	v_and_b32_e32 v221, 0xffff0000, v221
	s_waitcnt vmcnt(6)
	v_lshlrev_b32_e32 v230, 16, v224
	v_and_b32_e32 v231, 0xffff0000, v224
	v_lshlrev_b32_e32 v224, 16, v225
	v_and_b32_e32 v225, 0xffff0000, v225
	v_lshlrev_b32_e32 v228, 16, v222
	v_and_b32_e32 v229, 0xffff0000, v222
	v_lshlrev_b32_e32 v232, 16, v226
	v_and_b32_e32 v233, 0xffff0000, v226
	v_pk_add_f32 v[64:65], v[64:65], v[220:221]
	v_pk_add_f32 v[62:63], v[62:63], v[206:207]
	v_pk_add_f32 v[48:49], v[48:49], v[224:225]
	v_pk_add_f32 v[46:47], v[46:47], v[230:231]
	v_lshlrev_b32_e32 v222, 16, v223
	v_and_b32_e32 v223, 0xffff0000, v223
	v_lshlrev_b32_e32 v226, 16, v227
	v_and_b32_e32 v227, 0xffff0000, v227
	v_pk_add_f32 v[58:59], v[58:59], v[228:229]
	v_pk_add_f32 v[42:43], v[42:43], v[232:233]
	v_mul_f32_e32 v159, v63, v63
	v_mul_f32_e32 v161, v65, v65
	v_mul_f32_e32 v185, v47, v47
	v_mul_f32_e32 v187, v49, v49
	v_pk_add_f32 v[60:61], v[60:61], v[222:223]
	v_pk_add_f32 v[44:45], v[44:45], v[226:227]
	v_mul_f32_e32 v181, v59, v59
	v_mul_f32_e32 v189, v43, v43
	v_fmac_f32_e32 v159, v62, v62
	v_fmac_f32_e32 v161, v64, v64
	v_fmac_f32_e32 v185, v46, v46
	v_fmac_f32_e32 v187, v48, v48
	v_mul_f32_e32 v183, v61, v61
	v_mul_f32_e32 v191, v45, v45
	v_fmac_f32_e32 v181, v58, v58
	v_fmac_f32_e32 v189, v42, v42
	v_add_f32_e32 v159, v159, v161
	v_add_f32_e32 v161, v185, v187
	v_fmac_f32_e32 v183, v60, v60
	v_fmac_f32_e32 v191, v44, v44
	v_add_f32_e32 v159, v181, v159
	v_add_f32_e32 v161, v189, v161
	v_add_f32_e32 v159, v183, v159
	v_add_f32_e32 v161, v191, v161
	v_add_f32_e32 v159, v159, v161
	ds_bpermute_b32 v161, v155, v159
	s_waitcnt lgkmcnt(0)
	v_add_f32_e32 v159, v159, v161
	ds_bpermute_b32 v161, v157, v159
	s_and_saveexec_b64 s[50:51], s[4:5]
	s_cbranch_execz .LBB0_713
	s_waitcnt lgkmcnt(0)
	v_add_f32_e32 v159, v159, v161
	ds_write_b32 v218, v159 offset:2048
.LBB0_713:
	s_or_b64 exec, exec, s[50:51]
	s_waitcnt vmcnt(5)
	v_lshlrev_b32_e32 v206, 16, v150
	v_and_b32_e32 v207, 0xffff0000, v150
	v_lshlrev_b32_e32 v150, 16, v151
	v_and_b32_e32 v151, 0xffff0000, v151
	v_pk_add_f32 v[56:57], v[56:57], v[150:151]
	v_pk_add_f32 v[54:55], v[54:55], v[206:207]
	v_lshlrev_b32_e32 v220, 16, v152
	v_and_b32_e32 v221, 0xffff0000, v152
	v_mul_f32_e32 v159, v55, v55
	v_mul_f32_e32 v151, v57, v57
	v_pk_add_f32 v[50:51], v[50:51], v[220:221]
	v_fmac_f32_e32 v159, v54, v54
	v_fmac_f32_e32 v151, v56, v56
	v_lshlrev_b32_e32 v152, 16, v153
	v_and_b32_e32 v153, 0xffff0000, v153
	v_add_f32_e32 v150, v159, v151
	v_mul_f32_e32 v151, v51, v51
	v_pk_add_f32 v[52:53], v[52:53], v[152:153]
	v_fmac_f32_e32 v151, v50, v50
	v_add_f32_e32 v150, v151, v150
	v_mul_f32_e32 v151, v53, v53
	v_fmac_f32_e32 v151, v52, v52
	v_add_f32_e32 v159, v151, v150
	s_waitcnt vmcnt(4)
	v_lshlrev_b32_e32 v150, 16, v146
	v_and_b32_e32 v151, 0xffff0000, v146
	v_lshlrev_b32_e32 v146, 16, v147
	v_and_b32_e32 v147, 0xffff0000, v147
	v_pk_add_f32 v[32:33], v[32:33], v[146:147]
	v_pk_add_f32 v[30:31], v[30:31], v[150:151]
	v_lshlrev_b32_e32 v152, 16, v148
	v_and_b32_e32 v153, 0xffff0000, v148
	v_mul_f32_e32 v151, v31, v31
	v_mul_f32_e32 v147, v33, v33
	v_pk_add_f32 v[26:27], v[26:27], v[152:153]
	v_fmac_f32_e32 v151, v30, v30
	v_fmac_f32_e32 v147, v32, v32
	v_lshlrev_b32_e32 v148, 16, v149
	v_and_b32_e32 v149, 0xffff0000, v149
	v_add_f32_e32 v146, v151, v147
	v_mul_f32_e32 v147, v27, v27
	v_pk_add_f32 v[28:29], v[28:29], v[148:149]
	v_fmac_f32_e32 v147, v26, v26
	v_add_f32_e32 v146, v147, v146
	v_mul_f32_e32 v147, v29, v29
	v_fmac_f32_e32 v147, v28, v28
	v_add_f32_e32 v146, v147, v146
	v_add_f32_e32 v146, v159, v146
	ds_bpermute_b32 v147, v155, v146
	s_waitcnt lgkmcnt(0)
	v_add_f32_e32 v146, v146, v147
	ds_bpermute_b32 v147, v157, v146
	s_and_saveexec_b64 s[50:51], s[4:5]
	s_cbranch_execz .LBB0_715
	s_waitcnt lgkmcnt(0)
	v_add_f32_e32 v146, v146, v147
	ds_write_b32 v218, v146 offset:2304
.LBB0_715:
	s_or_b64 exec, exec, s[50:51]
	s_waitcnt vmcnt(3)
	v_lshlrev_b32_e32 v146, 16, v142
	s_waitcnt lgkmcnt(0)
	v_and_b32_e32 v147, 0xffff0000, v142
	v_lshlrev_b32_e32 v142, 16, v143
	v_and_b32_e32 v143, 0xffff0000, v143
	v_pk_add_f32 v[40:41], v[40:41], v[142:143]
	v_pk_add_f32 v[38:39], v[38:39], v[146:147]
	v_lshlrev_b32_e32 v148, 16, v144
	v_and_b32_e32 v149, 0xffff0000, v144
	v_mul_f32_e32 v147, v39, v39
	v_mul_f32_e32 v143, v41, v41
	v_pk_add_f32 v[34:35], v[34:35], v[148:149]
	v_fmac_f32_e32 v147, v38, v38
	v_fmac_f32_e32 v143, v40, v40
	v_lshlrev_b32_e32 v144, 16, v145
	v_and_b32_e32 v145, 0xffff0000, v145
	v_add_f32_e32 v142, v147, v143
	v_mul_f32_e32 v143, v35, v35
	v_pk_add_f32 v[36:37], v[36:37], v[144:145]
	v_fmac_f32_e32 v143, v34, v34
	v_add_f32_e32 v142, v143, v142
	v_mul_f32_e32 v143, v37, v37
	v_fmac_f32_e32 v143, v36, v36
	v_add_f32_e32 v146, v143, v142
	s_waitcnt vmcnt(2)
	v_lshlrev_b32_e32 v142, 16, v138
	v_and_b32_e32 v143, 0xffff0000, v138
	v_lshlrev_b32_e32 v138, 16, v139
	v_and_b32_e32 v139, 0xffff0000, v139
	v_pk_add_f32 v[16:17], v[16:17], v[138:139]
	v_pk_add_f32 v[14:15], v[14:15], v[142:143]
	v_lshlrev_b32_e32 v144, 16, v140
	v_and_b32_e32 v145, 0xffff0000, v140
	v_mul_f32_e32 v143, v15, v15
	v_mul_f32_e32 v139, v17, v17
	v_pk_add_f32 v[10:11], v[10:11], v[144:145]
	v_fmac_f32_e32 v143, v14, v14
	v_fmac_f32_e32 v139, v16, v16
	v_lshlrev_b32_e32 v140, 16, v141
	v_and_b32_e32 v141, 0xffff0000, v141
	v_add_f32_e32 v138, v143, v139
	v_mul_f32_e32 v139, v11, v11
	v_pk_add_f32 v[12:13], v[12:13], v[140:141]
	v_fmac_f32_e32 v139, v10, v10
	v_add_f32_e32 v138, v139, v138
	v_mul_f32_e32 v139, v13, v13
	v_fmac_f32_e32 v139, v12, v12
	v_add_f32_e32 v138, v139, v138
	v_add_f32_e32 v138, v146, v138
	ds_bpermute_b32 v139, v155, v138
	s_waitcnt lgkmcnt(0)
	v_add_f32_e32 v138, v138, v139
	ds_bpermute_b32 v139, v157, v138
	s_and_saveexec_b64 s[50:51], s[4:5]
	s_cbranch_execz .LBB0_717
	s_waitcnt lgkmcnt(0)
	v_add_f32_e32 v138, v138, v139
	ds_write_b32 v218, v138 offset:2560
.LBB0_717:
	s_or_b64 exec, exec, s[50:51]
	s_waitcnt vmcnt(1)
	v_lshlrev_b32_e32 v138, 16, v134
	s_waitcnt lgkmcnt(0)
	v_and_b32_e32 v139, 0xffff0000, v134
	v_lshlrev_b32_e32 v134, 16, v135
	v_and_b32_e32 v135, 0xffff0000, v135
	v_pk_add_f32 v[24:25], v[24:25], v[134:135]
	v_pk_add_f32 v[22:23], v[22:23], v[138:139]
	v_lshlrev_b32_e32 v140, 16, v136
	v_and_b32_e32 v141, 0xffff0000, v136
	v_mul_f32_e32 v139, v23, v23
	v_mul_f32_e32 v135, v25, v25
	v_pk_add_f32 v[18:19], v[18:19], v[140:141]
	v_fmac_f32_e32 v139, v22, v22
	v_fmac_f32_e32 v135, v24, v24
	v_lshlrev_b32_e32 v136, 16, v137
	v_and_b32_e32 v137, 0xffff0000, v137
	v_add_f32_e32 v134, v139, v135
	v_mul_f32_e32 v135, v19, v19
	v_pk_add_f32 v[20:21], v[20:21], v[136:137]
	v_fmac_f32_e32 v135, v18, v18
	v_add_f32_e32 v134, v135, v134
	v_mul_f32_e32 v135, v21, v21
	v_fmac_f32_e32 v135, v20, v20
	v_add_f32_e32 v138, v135, v134
	s_waitcnt vmcnt(0)
	v_lshlrev_b32_e32 v134, 16, v130
	v_and_b32_e32 v135, 0xffff0000, v130
	v_lshlrev_b32_e32 v130, 16, v131
	v_and_b32_e32 v131, 0xffff0000, v131
	v_pk_add_f32 v[8:9], v[8:9], v[130:131]
	v_pk_add_f32 v[6:7], v[6:7], v[134:135]
	v_lshlrev_b32_e32 v136, 16, v132
	v_and_b32_e32 v137, 0xffff0000, v132
	v_mul_f32_e32 v135, v7, v7
	v_mul_f32_e32 v131, v9, v9
	v_pk_add_f32 v[2:3], v[2:3], v[136:137]
	v_fmac_f32_e32 v135, v6, v6
	v_fmac_f32_e32 v131, v8, v8
	v_lshlrev_b32_e32 v132, 16, v133
	v_and_b32_e32 v133, 0xffff0000, v133
	v_add_f32_e32 v130, v135, v131
	v_mul_f32_e32 v131, v3, v3
	v_pk_add_f32 v[4:5], v[4:5], v[132:133]
	v_fmac_f32_e32 v131, v2, v2
	v_add_f32_e32 v130, v131, v130
	v_mul_f32_e32 v131, v5, v5
	v_fmac_f32_e32 v131, v4, v4
	v_add_f32_e32 v130, v131, v130
	v_add_f32_e32 v130, v138, v130
	ds_bpermute_b32 v131, v155, v130
	s_waitcnt lgkmcnt(0)
	v_add_f32_e32 v130, v130, v131
	ds_bpermute_b32 v131, v157, v130
	s_and_saveexec_b64 s[50:51], s[4:5]
	s_cbranch_execz .LBB0_719
	s_waitcnt lgkmcnt(0)
	v_add_f32_e32 v130, v130, v131
	ds_write_b32 v218, v130 offset:2816

.LBB0_739:
	s_or_b64 exec, exec, s[48:49]
	s_waitcnt lgkmcnt(0)
	s_barrier
	v_ashrrev_i32_e32 v183, 31, v182
	v_lshl_add_u64 v[130:131], v[182:183], 2, s[76:77]
	global_load_dwordx4 v[142:145], v[130:131], off
	global_load_dwordx4 v[138:141], v[130:131], off offset:16
	global_load_dwordx4 v[134:137], v[130:131], off offset:512
	global_load_dwordx4 v[146:149], v[130:131], off offset:528
	v_add_u32_e32 v181, 0x1000, v212
	ds_read2_b32 v[150:151], v181 offset1:16
	ds_read2_b32 v[152:153], v181 offset0:32 offset1:48
	ds_read2_b32 v[154:155], v181 offset0:128 offset1:144
	ds_read2_b32 v[156:157], v181 offset0:160 offset1:176
	v_lshlrev_b32_e32 v170, 2, v182
	v_lshl_add_u32 v170, v180, 12, v170
	s_waitcnt vmcnt(0) lgkmcnt(0)
	v_mov_b32_e32 v160, v150
	v_pk_mul_f32 v[126:127], v[126:127], v[160:161] op_sel_hi:[1,0]
	v_pk_mul_f32 v[128:129], v[128:129], v[160:161] op_sel_hi:[1,0]
	v_pk_mul_f32 v[126:127], v[126:127], v[142:143]
	v_pk_mul_f32 v[128:129], v[128:129], v[144:145]
	global_store_dwordx4 v170, v[126:129], s[78:79]
	v_pk_mul_f32 v[122:123], v[122:123], v[160:161] op_sel_hi:[1,0]
	v_pk_mul_f32 v[124:125], v[124:125], v[160:161] op_sel_hi:[1,0]
	v_pk_mul_f32 v[122:123], v[122:123], v[138:139]
	v_pk_mul_f32 v[124:125], v[124:125], v[140:141]
	global_store_dwordx4 v170, v[122:125], s[78:79] offset:16
	v_pk_mul_f32 v[110:111], v[110:111], v[160:161] op_sel_hi:[1,0]
	v_pk_mul_f32 v[112:113], v[112:113], v[160:161] op_sel_hi:[1,0]
	v_pk_mul_f32 v[110:111], v[110:111], v[134:135]
	v_pk_mul_f32 v[112:113], v[112:113], v[136:137]
	global_store_dwordx4 v170, v[110:113], s[78:79] offset:512
	v_pk_mul_f32 v[106:107], v[106:107], v[160:161] op_sel_hi:[1,0]
	v_pk_mul_f32 v[108:109], v[108:109], v[160:161] op_sel_hi:[1,0]
	v_pk_mul_f32 v[106:107], v[106:107], v[146:147]
	v_pk_mul_f32 v[108:109], v[108:109], v[148:149]
	global_store_dwordx4 v170, v[106:109], s[78:79] offset:528
	v_mov_b32_e32 v160, v151
	v_add_u32_e32 v158, 0x10000, v170
	v_pk_mul_f32 v[118:119], v[118:119], v[160:161] op_sel_hi:[1,0]
	v_pk_mul_f32 v[120:121], v[120:121], v[160:161] op_sel_hi:[1,0]
	v_pk_mul_f32 v[118:119], v[118:119], v[142:143]
	v_pk_mul_f32 v[120:121], v[120:121], v[144:145]
	global_store_dwordx4 v158, v[118:121], s[78:79]
	v_pk_mul_f32 v[114:115], v[114:115], v[160:161] op_sel_hi:[1,0]
	v_pk_mul_f32 v[116:117], v[116:117], v[160:161] op_sel_hi:[1,0]
	v_pk_mul_f32 v[114:115], v[114:115], v[138:139]
	v_pk_mul_f32 v[116:117], v[116:117], v[140:141]
	global_store_dwordx4 v158, v[114:117], s[78:79] offset:16
	v_pk_mul_f32 v[94:95], v[94:95], v[160:161] op_sel_hi:[1,0]
	v_pk_mul_f32 v[96:97], v[96:97], v[160:161] op_sel_hi:[1,0]
	v_pk_mul_f32 v[94:95], v[94:95], v[134:135]
	v_pk_mul_f32 v[96:97], v[96:97], v[136:137]
	global_store_dwordx4 v158, v[94:97], s[78:79] offset:512
	v_pk_mul_f32 v[90:91], v[90:91], v[160:161] op_sel_hi:[1,0]
	v_pk_mul_f32 v[92:93], v[92:93], v[160:161] op_sel_hi:[1,0]
	v_pk_mul_f32 v[90:91], v[90:91], v[146:147]
	v_pk_mul_f32 v[92:93], v[92:93], v[148:149]
	global_store_dwordx4 v158, v[90:93], s[78:79] offset:528
	v_mov_b32_e32 v160, v152
	v_add_u32_e32 v158, 0x20000, v170
	v_pk_mul_f32 v[102:103], v[102:103], v[160:161] op_sel_hi:[1,0]
	v_pk_mul_f32 v[104:105], v[104:105], v[160:161] op_sel_hi:[1,0]
	v_pk_mul_f32 v[102:103], v[102:103], v[142:143]
	v_pk_mul_f32 v[104:105], v[104:105], v[144:145]
	global_store_dwordx4 v158, v[102:105], s[78:79]
	v_pk_mul_f32 v[98:99], v[98:99], v[160:161] op_sel_hi:[1,0]
	v_pk_mul_f32 v[100:101], v[100:101], v[160:161] op_sel_hi:[1,0]
	v_pk_mul_f32 v[98:99], v[98:99], v[138:139]
	v_pk_mul_f32 v[100:101], v[100:101], v[140:141]
	global_store_dwordx4 v158, v[98:101], s[78:79] offset:16
	v_pk_mul_f32 v[78:79], v[78:79], v[160:161] op_sel_hi:[1,0]
	v_pk_mul_f32 v[80:81], v[80:81], v[160:161] op_sel_hi:[1,0]
	v_pk_mul_f32 v[78:79], v[78:79], v[134:135]
	v_pk_mul_f32 v[80:81], v[80:81], v[136:137]
	global_store_dwordx4 v158, v[78:81], s[78:79] offset:512
	v_pk_mul_f32 v[74:75], v[74:75], v[160:161] op_sel_hi:[1,0]
	v_pk_mul_f32 v[76:77], v[76:77], v[160:161] op_sel_hi:[1,0]
	v_pk_mul_f32 v[74:75], v[74:75], v[146:147]
	v_pk_mul_f32 v[76:77], v[76:77], v[148:149]
	global_store_dwordx4 v158, v[74:77], s[78:79] offset:528
	v_mov_b32_e32 v160, v153
	v_add_u32_e32 v158, 0x30000, v170
	v_pk_mul_f32 v[86:87], v[86:87], v[160:161] op_sel_hi:[1,0]
	v_pk_mul_f32 v[88:89], v[88:89], v[160:161] op_sel_hi:[1,0]
	v_pk_mul_f32 v[86:87], v[86:87], v[142:143]
	v_pk_mul_f32 v[88:89], v[88:89], v[144:145]
	global_store_dwordx4 v158, v[86:89], s[78:79]
	v_pk_mul_f32 v[82:83], v[82:83], v[160:161] op_sel_hi:[1,0]
	v_pk_mul_f32 v[84:85], v[84:85], v[160:161] op_sel_hi:[1,0]
	v_pk_mul_f32 v[82:83], v[82:83], v[138:139]
	v_pk_mul_f32 v[84:85], v[84:85], v[140:141]
	global_store_dwordx4 v158, v[82:85], s[78:79] offset:16
	v_pk_mul_f32 v[70:71], v[70:71], v[160:161] op_sel_hi:[1,0]
	v_pk_mul_f32 v[72:73], v[72:73], v[160:161] op_sel_hi:[1,0]
	v_pk_mul_f32 v[70:71], v[70:71], v[134:135]
	v_pk_mul_f32 v[72:73], v[72:73], v[136:137]
	global_store_dwordx4 v158, v[70:73], s[78:79] offset:512
	v_pk_mul_f32 v[66:67], v[66:67], v[160:161] op_sel_hi:[1,0]
	v_pk_mul_f32 v[68:69], v[68:69], v[160:161] op_sel_hi:[1,0]
	v_pk_mul_f32 v[66:67], v[66:67], v[146:147]
	v_pk_mul_f32 v[68:69], v[68:69], v[148:149]
	global_store_dwordx4 v158, v[66:69], s[78:79] offset:528
	v_mov_b32_e32 v160, v154
	v_add_u32_e32 v158, 0x80000, v170
	v_pk_mul_f32 v[62:63], v[62:63], v[160:161] op_sel_hi:[1,0]
	v_pk_mul_f32 v[64:65], v[64:65], v[160:161] op_sel_hi:[1,0]
	v_pk_mul_f32 v[62:63], v[62:63], v[142:143]
	v_pk_mul_f32 v[64:65], v[64:65], v[144:145]
	global_store_dwordx4 v158, v[62:65], s[78:79]
	v_pk_mul_f32 v[58:59], v[58:59], v[160:161] op_sel_hi:[1,0]
	v_pk_mul_f32 v[60:61], v[60:61], v[160:161] op_sel_hi:[1,0]
	v_pk_mul_f32 v[58:59], v[58:59], v[138:139]
	v_pk_mul_f32 v[60:61], v[60:61], v[140:141]
	global_store_dwordx4 v158, v[58:61], s[78:79] offset:16
	v_pk_mul_f32 v[46:47], v[46:47], v[160:161] op_sel_hi:[1,0]
	v_pk_mul_f32 v[48:49], v[48:49], v[160:161] op_sel_hi:[1,0]
	v_pk_mul_f32 v[46:47], v[46:47], v[134:135]
	v_pk_mul_f32 v[48:49], v[48:49], v[136:137]
	global_store_dwordx4 v158, v[46:49], s[78:79] offset:512
	v_pk_mul_f32 v[42:43], v[42:43], v[160:161] op_sel_hi:[1,0]
	v_pk_mul_f32 v[44:45], v[44:45], v[160:161] op_sel_hi:[1,0]
	v_pk_mul_f32 v[42:43], v[42:43], v[146:147]
	v_pk_mul_f32 v[44:45], v[44:45], v[148:149]
	global_store_dwordx4 v158, v[42:45], s[78:79] offset:528
	v_mov_b32_e32 v160, v155
	v_add_u32_e32 v158, 0x90000, v170
	v_pk_mul_f32 v[54:55], v[54:55], v[160:161] op_sel_hi:[1,0]
	v_pk_mul_f32 v[56:57], v[56:57], v[160:161] op_sel_hi:[1,0]
	v_pk_mul_f32 v[54:55], v[54:55], v[142:143]
	v_pk_mul_f32 v[56:57], v[56:57], v[144:145]
	global_store_dwordx4 v158, v[54:57], s[78:79]
	v_pk_mul_f32 v[50:51], v[50:51], v[160:161] op_sel_hi:[1,0]
	v_pk_mul_f32 v[52:53], v[52:53], v[160:161] op_sel_hi:[1,0]
	v_pk_mul_f32 v[50:51], v[50:51], v[138:139]
	v_pk_mul_f32 v[52:53], v[52:53], v[140:141]
	global_store_dwordx4 v158, v[50:53], s[78:79] offset:16
	v_pk_mul_f32 v[30:31], v[30:31], v[160:161] op_sel_hi:[1,0]
	v_pk_mul_f32 v[32:33], v[32:33], v[160:161] op_sel_hi:[1,0]
	v_pk_mul_f32 v[30:31], v[30:31], v[134:135]
	v_pk_mul_f32 v[32:33], v[32:33], v[136:137]
	global_store_dwordx4 v158, v[30:33], s[78:79] offset:512
	v_pk_mul_f32 v[26:27], v[26:27], v[160:161] op_sel_hi:[1,0]
	v_pk_mul_f32 v[28:29], v[28:29], v[160:161] op_sel_hi:[1,0]
	v_pk_mul_f32 v[26:27], v[26:27], v[146:147]
	v_pk_mul_f32 v[28:29], v[28:29], v[148:149]
	global_store_dwordx4 v158, v[26:29], s[78:79] offset:528
	v_mov_b32_e32 v160, v156
	v_add_u32_e32 v158, 0xa0000, v170
	v_pk_mul_f32 v[38:39], v[38:39], v[160:161] op_sel_hi:[1,0]
	v_pk_mul_f32 v[40:41], v[40:41], v[160:161] op_sel_hi:[1,0]
	v_pk_mul_f32 v[38:39], v[38:39], v[142:143]
	v_pk_mul_f32 v[40:41], v[40:41], v[144:145]
	global_store_dwordx4 v158, v[38:41], s[78:79]
	v_pk_mul_f32 v[34:35], v[34:35], v[160:161] op_sel_hi:[1,0]
	v_pk_mul_f32 v[36:37], v[36:37], v[160:161] op_sel_hi:[1,0]
	v_pk_mul_f32 v[34:35], v[34:35], v[138:139]
	v_pk_mul_f32 v[36:37], v[36:37], v[140:141]
	global_store_dwordx4 v158, v[34:37], s[78:79] offset:16
	v_pk_mul_f32 v[14:15], v[14:15], v[160:161] op_sel_hi:[1,0]
	v_pk_mul_f32 v[16:17], v[16:17], v[160:161] op_sel_hi:[1,0]
	v_pk_mul_f32 v[14:15], v[14:15], v[134:135]
	v_pk_mul_f32 v[16:17], v[16:17], v[136:137]
	global_store_dwordx4 v158, v[14:17], s[78:79] offset:512
	v_pk_mul_f32 v[10:11], v[10:11], v[160:161] op_sel_hi:[1,0]
	v_pk_mul_f32 v[12:13], v[12:13], v[160:161] op_sel_hi:[1,0]
	v_pk_mul_f32 v[10:11], v[10:11], v[146:147]
	v_pk_mul_f32 v[12:13], v[12:13], v[148:149]
	global_store_dwordx4 v158, v[10:13], s[78:79] offset:528
	v_mov_b32_e32 v160, v157
	v_add_u32_e32 v158, 0xb0000, v170
	v_pk_mul_f32 v[22:23], v[22:23], v[160:161] op_sel_hi:[1,0]
	v_pk_mul_f32 v[24:25], v[24:25], v[160:161] op_sel_hi:[1,0]
	v_pk_mul_f32 v[22:23], v[22:23], v[142:143]
	v_pk_mul_f32 v[24:25], v[24:25], v[144:145]
	global_store_dwordx4 v158, v[22:25], s[78:79]
	v_pk_mul_f32 v[18:19], v[18:19], v[160:161] op_sel_hi:[1,0]
	v_pk_mul_f32 v[20:21], v[20:21], v[160:161] op_sel_hi:[1,0]
	v_pk_mul_f32 v[18:19], v[18:19], v[138:139]
	v_pk_mul_f32 v[20:21], v[20:21], v[140:141]
	global_store_dwordx4 v158, v[18:21], s[78:79] offset:16
	v_pk_mul_f32 v[6:7], v[6:7], v[160:161] op_sel_hi:[1,0]
	v_pk_mul_f32 v[8:9], v[8:9], v[160:161] op_sel_hi:[1,0]
	v_pk_mul_f32 v[6:7], v[6:7], v[134:135]
	v_pk_mul_f32 v[8:9], v[8:9], v[136:137]
	global_store_dwordx4 v158, v[6:9], s[78:79] offset:512
	v_pk_mul_f32 v[2:3], v[2:3], v[160:161] op_sel_hi:[1,0]
	v_pk_mul_f32 v[4:5], v[4:5], v[160:161] op_sel_hi:[1,0]
	v_pk_mul_f32 v[2:3], v[2:3], v[146:147]
	v_pk_mul_f32 v[4:5], v[4:5], v[148:149]
	global_store_dwordx4 v158, v[2:5], s[78:79] offset:528
